# FFN-down EpiResid epilogue rewritten: two straight-line paths (f32-base+bf16 copy+sumsq / bf16-base+f32 nt out), base loads hoisted-rolled 16 in flight, shuffles batched
# speedup vs baseline: 1.0197x; 1.0197x over previous
.LBB0_363:
	s_lshl_b32 s0, s11, 8
	s_add_i32 s0, s0, s55
	v_and_b32_e32 v171, 15, v206
	v_or_b32_e32 v171, s0, v171
	s_lshl_b32 s2, s10, 8
	s_or_b32 s2, s2, s56
	v_bfe_u32 v146, v206, 4, 2
	v_lshl_or_b32 v146, v146, 3, s2
	v_lshlrev_b32_e32 v158, 11, v171
	v_lshl_add_u32 v158, v146, 1, v158
	v_add_u32_e32 v159, 0x8000, v158
	v_add_u32_e32 v160, 0x10000, v158
	v_add_u32_e32 v161, 0x18000, v158
	v_add_u32_e32 v162, 0x40000, v158
	v_add_u32_e32 v163, 0x48000, v158
	v_add_u32_e32 v204, 0x50000, v158
	v_add_u32_e32 v205, 0x58000, v158
	s_and_b64 vcc, exec, s[16:17]
	s_cbranch_vccnz .Ldown_epi_r1
	v_lshlrev_b32_e32 v212, 1, v158
	v_lshlrev_b32_e32 v213, 1, v159
	v_lshlrev_b32_e32 v214, 1, v160
	v_lshlrev_b32_e32 v215, 1, v161
	global_load_dwordx4 v[172:175], v212, s[88:89]
	global_load_dwordx4 v[176:179], v212, s[88:89] offset:16
	global_load_dwordx4 v[180:183], v212, s[88:89] offset:512
	global_load_dwordx4 v[184:187], v212, s[88:89] offset:528
	global_load_dwordx4 v[188:191], v213, s[88:89]
	global_load_dwordx4 v[192:195], v213, s[88:89] offset:16
	global_load_dwordx4 v[196:199], v213, s[88:89] offset:512
	global_load_dwordx4 v[200:203], v213, s[88:89] offset:528
	global_load_dwordx4 v[218:221], v214, s[88:89]
	global_load_dwordx4 v[222:225], v214, s[88:89] offset:16
	global_load_dwordx4 v[226:229], v214, s[88:89] offset:512
	global_load_dwordx4 v[230:233], v214, s[88:89] offset:528
	global_load_dwordx4 v[128:131], v215, s[88:89]
	global_load_dwordx4 v[132:135], v215, s[88:89] offset:16
	global_load_dwordx4 v[150:153], v215, s[88:89] offset:512
	global_load_dwordx4 v[154:157], v215, s[88:89] offset:528
	s_waitcnt vmcnt(14)
	v_fma_f32 v124, v124, 0.5, v172
	v_fma_f32 v125, v125, 0.5, v173
	v_fma_f32 v126, v126, 0.5, v174
	v_fma_f32 v127, v127, 0.5, v175
	v_fma_f32 v120, v120, 0.5, v176
	v_fma_f32 v121, v121, 0.5, v177
	v_fma_f32 v122, v122, 0.5, v178
	v_fma_f32 v123, v123, 0.5, v179
	v_lshlrev_b32_e32 v208, 1, v162
	v_cvt_pk_bf16_f32 v212, v124, v125
	v_cvt_pk_bf16_f32 v213, v126, v127
	v_cvt_pk_bf16_f32 v214, v120, v121
	v_cvt_pk_bf16_f32 v215, v122, v123
	global_load_dwordx4 v[172:175], v208, s[88:89]
	global_load_dwordx4 v[176:179], v208, s[88:89] offset:16
	global_store_dwordx4 v158, v[212:215], s[20:21]
	v_mul_f32_e32 v146, v125, v125
	v_mul_f32_e32 v147, v127, v127
	v_fmac_f32_e32 v146, v124, v124
	v_fmac_f32_e32 v147, v126, v126
	v_add_f32_e32 v146, v146, v147
	v_mul_f32_e32 v147, v121, v121
	v_mul_f32_e32 v170, v123, v123
	v_fmac_f32_e32 v147, v120, v120
	v_fmac_f32_e32 v170, v122, v122
	v_add_f32_e32 v147, v147, v170
	v_add_f32_e32 v124, v146, v147
	s_waitcnt vmcnt(15)
	v_fma_f32 v116, v116, 0.5, v180
	v_fma_f32 v117, v117, 0.5, v181
	v_fma_f32 v118, v118, 0.5, v182
	v_fma_f32 v119, v119, 0.5, v183
	v_fma_f32 v112, v112, 0.5, v184
	v_fma_f32 v113, v113, 0.5, v185
	v_fma_f32 v114, v114, 0.5, v186
	v_fma_f32 v115, v115, 0.5, v187
	v_lshlrev_b32_e32 v209, 1, v162
	v_cvt_pk_bf16_f32 v164, v116, v117
	v_cvt_pk_bf16_f32 v165, v118, v119
	v_cvt_pk_bf16_f32 v166, v112, v113
	v_cvt_pk_bf16_f32 v167, v114, v115
	global_load_dwordx4 v[180:183], v209, s[88:89] offset:512
	global_load_dwordx4 v[184:187], v209, s[88:89] offset:528
	global_store_dwordx4 v158, v[164:167], s[20:21] offset:256
	v_mul_f32_e32 v146, v117, v117
	v_mul_f32_e32 v147, v119, v119
	v_fmac_f32_e32 v146, v116, v116
	v_fmac_f32_e32 v147, v118, v118
	v_add_f32_e32 v146, v146, v147
	v_mul_f32_e32 v147, v113, v113
	v_mul_f32_e32 v170, v115, v115
	v_fmac_f32_e32 v147, v112, v112
	v_fmac_f32_e32 v170, v114, v114
	v_add_f32_e32 v147, v147, v170
	v_add_f32_e32 v146, v146, v147
	v_add_f32_e32 v112, v124, v146
	s_waitcnt vmcnt(16)
	v_fma_f32 v108, v108, 0.5, v188
	v_fma_f32 v109, v109, 0.5, v189
	v_fma_f32 v110, v110, 0.5, v190
	v_fma_f32 v111, v111, 0.5, v191
	v_fma_f32 v104, v104, 0.5, v192
	v_fma_f32 v105, v105, 0.5, v193
	v_fma_f32 v106, v106, 0.5, v194
	v_fma_f32 v107, v107, 0.5, v195
	v_lshlrev_b32_e32 v208, 1, v163
	v_cvt_pk_bf16_f32 v212, v108, v109
	v_cvt_pk_bf16_f32 v213, v110, v111
	v_cvt_pk_bf16_f32 v214, v104, v105
	v_cvt_pk_bf16_f32 v215, v106, v107
	global_load_dwordx4 v[188:191], v208, s[88:89]
	global_load_dwordx4 v[192:195], v208, s[88:89] offset:16
	global_store_dwordx4 v159, v[212:215], s[20:21]
	v_mul_f32_e32 v146, v109, v109
	v_mul_f32_e32 v147, v111, v111
	v_fmac_f32_e32 v146, v108, v108
	v_fmac_f32_e32 v147, v110, v110
	v_add_f32_e32 v146, v146, v147
	v_mul_f32_e32 v147, v105, v105
	v_mul_f32_e32 v170, v107, v107
	v_fmac_f32_e32 v147, v104, v104
	v_fmac_f32_e32 v170, v106, v106
	v_add_f32_e32 v147, v147, v170
	v_add_f32_e32 v108, v146, v147
	s_waitcnt vmcnt(17)
	v_fma_f32 v100, v100, 0.5, v196
	v_fma_f32 v101, v101, 0.5, v197
	v_fma_f32 v102, v102, 0.5, v198
	v_fma_f32 v103, v103, 0.5, v199
	v_fma_f32 v96, v96, 0.5, v200
	v_fma_f32 v97, v97, 0.5, v201
	v_fma_f32 v98, v98, 0.5, v202
	v_fma_f32 v99, v99, 0.5, v203
	v_lshlrev_b32_e32 v209, 1, v163
	v_cvt_pk_bf16_f32 v164, v100, v101
	v_cvt_pk_bf16_f32 v165, v102, v103
	v_cvt_pk_bf16_f32 v166, v96, v97
	v_cvt_pk_bf16_f32 v167, v98, v99
	global_load_dwordx4 v[196:199], v209, s[88:89] offset:512
	global_load_dwordx4 v[200:203], v209, s[88:89] offset:528
	global_store_dwordx4 v159, v[164:167], s[20:21] offset:256
	v_mul_f32_e32 v146, v101, v101
	v_mul_f32_e32 v147, v103, v103
	v_fmac_f32_e32 v146, v100, v100
	v_fmac_f32_e32 v147, v102, v102
	v_add_f32_e32 v146, v146, v147
	v_mul_f32_e32 v147, v97, v97
	v_mul_f32_e32 v170, v99, v99
	v_fmac_f32_e32 v147, v96, v96
	v_fmac_f32_e32 v170, v98, v98
	v_add_f32_e32 v147, v147, v170
	v_add_f32_e32 v146, v146, v147
	v_add_f32_e32 v96, v108, v146
	s_waitcnt vmcnt(18)
	v_fma_f32 v92, v92, 0.5, v218
	v_fma_f32 v93, v93, 0.5, v219
	v_fma_f32 v94, v94, 0.5, v220
	v_fma_f32 v95, v95, 0.5, v221
	v_fma_f32 v88, v88, 0.5, v222
	v_fma_f32 v89, v89, 0.5, v223
	v_fma_f32 v90, v90, 0.5, v224
	v_fma_f32 v91, v91, 0.5, v225
	v_lshlrev_b32_e32 v208, 1, v204
	v_cvt_pk_bf16_f32 v212, v92, v93
	v_cvt_pk_bf16_f32 v213, v94, v95
	v_cvt_pk_bf16_f32 v214, v88, v89
	v_cvt_pk_bf16_f32 v215, v90, v91
	global_load_dwordx4 v[218:221], v208, s[88:89]
	global_load_dwordx4 v[222:225], v208, s[88:89] offset:16
	global_store_dwordx4 v160, v[212:215], s[20:21]
	v_mul_f32_e32 v146, v93, v93
	v_mul_f32_e32 v147, v95, v95
	v_fmac_f32_e32 v146, v92, v92
	v_fmac_f32_e32 v147, v94, v94
	v_add_f32_e32 v146, v146, v147
	v_mul_f32_e32 v147, v89, v89
	v_mul_f32_e32 v170, v91, v91
	v_fmac_f32_e32 v147, v88, v88
	v_fmac_f32_e32 v170, v90, v90
	v_add_f32_e32 v147, v147, v170
	v_add_f32_e32 v92, v146, v147
	s_waitcnt vmcnt(19)
	v_fma_f32 v84, v84, 0.5, v226
	v_fma_f32 v85, v85, 0.5, v227
	v_fma_f32 v86, v86, 0.5, v228
	v_fma_f32 v87, v87, 0.5, v229
	v_fma_f32 v80, v80, 0.5, v230
	v_fma_f32 v81, v81, 0.5, v231
	v_fma_f32 v82, v82, 0.5, v232
	v_fma_f32 v83, v83, 0.5, v233
	v_lshlrev_b32_e32 v209, 1, v204
	v_cvt_pk_bf16_f32 v164, v84, v85
	v_cvt_pk_bf16_f32 v165, v86, v87
	v_cvt_pk_bf16_f32 v166, v80, v81
	v_cvt_pk_bf16_f32 v167, v82, v83
	global_load_dwordx4 v[226:229], v209, s[88:89] offset:512
	global_load_dwordx4 v[230:233], v209, s[88:89] offset:528
	global_store_dwordx4 v160, v[164:167], s[20:21] offset:256
	v_mul_f32_e32 v146, v85, v85
	v_mul_f32_e32 v147, v87, v87
	v_fmac_f32_e32 v146, v84, v84
	v_fmac_f32_e32 v147, v86, v86
	v_add_f32_e32 v146, v146, v147
	v_mul_f32_e32 v147, v81, v81
	v_mul_f32_e32 v170, v83, v83
	v_fmac_f32_e32 v147, v80, v80
	v_fmac_f32_e32 v170, v82, v82
	v_add_f32_e32 v147, v147, v170
	v_add_f32_e32 v146, v146, v147
	v_add_f32_e32 v80, v92, v146
	s_waitcnt vmcnt(20)
	v_fma_f32 v76, v76, 0.5, v128
	v_fma_f32 v77, v77, 0.5, v129
	v_fma_f32 v78, v78, 0.5, v130
	v_fma_f32 v79, v79, 0.5, v131
	v_fma_f32 v72, v72, 0.5, v132
	v_fma_f32 v73, v73, 0.5, v133
	v_fma_f32 v74, v74, 0.5, v134
	v_fma_f32 v75, v75, 0.5, v135
	v_lshlrev_b32_e32 v208, 1, v205
	v_cvt_pk_bf16_f32 v212, v76, v77
	v_cvt_pk_bf16_f32 v213, v78, v79
	v_cvt_pk_bf16_f32 v214, v72, v73
	v_cvt_pk_bf16_f32 v215, v74, v75
	global_load_dwordx4 v[128:131], v208, s[88:89]
	global_load_dwordx4 v[132:135], v208, s[88:89] offset:16
	global_store_dwordx4 v161, v[212:215], s[20:21]
	v_mul_f32_e32 v146, v77, v77
	v_mul_f32_e32 v147, v79, v79
	v_fmac_f32_e32 v146, v76, v76
	v_fmac_f32_e32 v147, v78, v78
	v_add_f32_e32 v146, v146, v147
	v_mul_f32_e32 v147, v73, v73
	v_mul_f32_e32 v170, v75, v75
	v_fmac_f32_e32 v147, v72, v72
	v_fmac_f32_e32 v170, v74, v74
	v_add_f32_e32 v147, v147, v170
	v_add_f32_e32 v76, v146, v147
	s_waitcnt vmcnt(21)
	v_fma_f32 v68, v68, 0.5, v150
	v_fma_f32 v69, v69, 0.5, v151
	v_fma_f32 v70, v70, 0.5, v152
	v_fma_f32 v71, v71, 0.5, v153
	v_fma_f32 v64, v64, 0.5, v154
	v_fma_f32 v65, v65, 0.5, v155
	v_fma_f32 v66, v66, 0.5, v156
	v_fma_f32 v67, v67, 0.5, v157
	v_lshlrev_b32_e32 v209, 1, v205
	v_cvt_pk_bf16_f32 v164, v68, v69
	v_cvt_pk_bf16_f32 v165, v70, v71
	v_cvt_pk_bf16_f32 v166, v64, v65
	v_cvt_pk_bf16_f32 v167, v66, v67
	global_load_dwordx4 v[150:153], v209, s[88:89] offset:512
	global_load_dwordx4 v[154:157], v209, s[88:89] offset:528
	global_store_dwordx4 v161, v[164:167], s[20:21] offset:256
	v_mul_f32_e32 v146, v69, v69
	v_mul_f32_e32 v147, v71, v71
	v_fmac_f32_e32 v146, v68, v68
	v_fmac_f32_e32 v147, v70, v70
	v_add_f32_e32 v146, v146, v147
	v_mul_f32_e32 v147, v65, v65
	v_mul_f32_e32 v170, v67, v67
	v_fmac_f32_e32 v147, v64, v64
	v_fmac_f32_e32 v170, v66, v66
	v_add_f32_e32 v147, v147, v170
	v_add_f32_e32 v146, v146, v147
	v_add_f32_e32 v64, v76, v146
	s_waitcnt vmcnt(21)
	v_fma_f32 v60, v60, 0.5, v172
	v_fma_f32 v61, v61, 0.5, v173
	v_fma_f32 v62, v62, 0.5, v174
	v_fma_f32 v63, v63, 0.5, v175
	v_fma_f32 v56, v56, 0.5, v176
	v_fma_f32 v57, v57, 0.5, v177
	v_fma_f32 v58, v58, 0.5, v178
	v_fma_f32 v59, v59, 0.5, v179
	v_cvt_pk_bf16_f32 v212, v60, v61
	v_cvt_pk_bf16_f32 v213, v62, v63
	v_cvt_pk_bf16_f32 v214, v56, v57
	v_cvt_pk_bf16_f32 v215, v58, v59
	global_store_dwordx4 v162, v[212:215], s[20:21]
	v_mul_f32_e32 v146, v61, v61
	v_mul_f32_e32 v147, v63, v63
	v_fmac_f32_e32 v146, v60, v60
	v_fmac_f32_e32 v147, v62, v62
	v_add_f32_e32 v146, v146, v147
	v_mul_f32_e32 v147, v57, v57
	v_mul_f32_e32 v170, v59, v59
	v_fmac_f32_e32 v147, v56, v56
	v_fmac_f32_e32 v170, v58, v58
	v_add_f32_e32 v147, v147, v170
	v_add_f32_e32 v60, v146, v147
	s_waitcnt vmcnt(19)
	v_fma_f32 v52, v52, 0.5, v180
	v_fma_f32 v53, v53, 0.5, v181
	v_fma_f32 v54, v54, 0.5, v182
	v_fma_f32 v55, v55, 0.5, v183
	v_fma_f32 v48, v48, 0.5, v184
	v_fma_f32 v49, v49, 0.5, v185
	v_fma_f32 v50, v50, 0.5, v186
	v_fma_f32 v51, v51, 0.5, v187
	v_cvt_pk_bf16_f32 v164, v52, v53
	v_cvt_pk_bf16_f32 v165, v54, v55
	v_cvt_pk_bf16_f32 v166, v48, v49
	v_cvt_pk_bf16_f32 v167, v50, v51
	global_store_dwordx4 v162, v[164:167], s[20:21] offset:256
	v_mul_f32_e32 v146, v53, v53
	v_mul_f32_e32 v147, v55, v55
	v_fmac_f32_e32 v146, v52, v52
	v_fmac_f32_e32 v147, v54, v54
	v_add_f32_e32 v146, v146, v147
	v_mul_f32_e32 v147, v49, v49
	v_mul_f32_e32 v170, v51, v51
	v_fmac_f32_e32 v147, v48, v48
	v_fmac_f32_e32 v170, v50, v50
	v_add_f32_e32 v147, v147, v170
	v_add_f32_e32 v146, v146, v147
	v_add_f32_e32 v48, v60, v146
	s_waitcnt vmcnt(17)
	v_fma_f32 v44, v44, 0.5, v188
	v_fma_f32 v45, v45, 0.5, v189
	v_fma_f32 v46, v46, 0.5, v190
	v_fma_f32 v47, v47, 0.5, v191
	v_fma_f32 v40, v40, 0.5, v192
	v_fma_f32 v41, v41, 0.5, v193
	v_fma_f32 v42, v42, 0.5, v194
	v_fma_f32 v43, v43, 0.5, v195
	v_cvt_pk_bf16_f32 v212, v44, v45
	v_cvt_pk_bf16_f32 v213, v46, v47
	v_cvt_pk_bf16_f32 v214, v40, v41
	v_cvt_pk_bf16_f32 v215, v42, v43
	global_store_dwordx4 v163, v[212:215], s[20:21]
	v_mul_f32_e32 v146, v45, v45
	v_mul_f32_e32 v147, v47, v47
	v_fmac_f32_e32 v146, v44, v44
	v_fmac_f32_e32 v147, v46, v46
	v_add_f32_e32 v146, v146, v147
	v_mul_f32_e32 v147, v41, v41
	v_mul_f32_e32 v170, v43, v43
	v_fmac_f32_e32 v147, v40, v40
	v_fmac_f32_e32 v170, v42, v42
	v_add_f32_e32 v147, v147, v170
	v_add_f32_e32 v44, v146, v147
	s_waitcnt vmcnt(15)
	v_fma_f32 v36, v36, 0.5, v196
	v_fma_f32 v37, v37, 0.5, v197
	v_fma_f32 v38, v38, 0.5, v198
	v_fma_f32 v39, v39, 0.5, v199
	v_fma_f32 v32, v32, 0.5, v200
	v_fma_f32 v33, v33, 0.5, v201
	v_fma_f32 v34, v34, 0.5, v202
	v_fma_f32 v35, v35, 0.5, v203
	v_cvt_pk_bf16_f32 v164, v36, v37
	v_cvt_pk_bf16_f32 v165, v38, v39
	v_cvt_pk_bf16_f32 v166, v32, v33
	v_cvt_pk_bf16_f32 v167, v34, v35
	global_store_dwordx4 v163, v[164:167], s[20:21] offset:256
	v_mul_f32_e32 v146, v37, v37
	v_mul_f32_e32 v147, v39, v39
	v_fmac_f32_e32 v146, v36, v36
	v_fmac_f32_e32 v147, v38, v38
	v_add_f32_e32 v146, v146, v147
	v_mul_f32_e32 v147, v33, v33
	v_mul_f32_e32 v170, v35, v35
	v_fmac_f32_e32 v147, v32, v32
	v_fmac_f32_e32 v170, v34, v34
	v_add_f32_e32 v147, v147, v170
	v_add_f32_e32 v146, v146, v147
	v_add_f32_e32 v32, v44, v146
	s_waitcnt vmcnt(13)
	v_fma_f32 v28, v28, 0.5, v218
	v_fma_f32 v29, v29, 0.5, v219
	v_fma_f32 v30, v30, 0.5, v220
	v_fma_f32 v31, v31, 0.5, v221
	v_fma_f32 v24, v24, 0.5, v222
	v_fma_f32 v25, v25, 0.5, v223
	v_fma_f32 v26, v26, 0.5, v224
	v_fma_f32 v27, v27, 0.5, v225
	v_cvt_pk_bf16_f32 v212, v28, v29
	v_cvt_pk_bf16_f32 v213, v30, v31
	v_cvt_pk_bf16_f32 v214, v24, v25
	v_cvt_pk_bf16_f32 v215, v26, v27
	global_store_dwordx4 v204, v[212:215], s[20:21]
	v_mul_f32_e32 v146, v29, v29
	v_mul_f32_e32 v147, v31, v31
	v_fmac_f32_e32 v146, v28, v28
	v_fmac_f32_e32 v147, v30, v30
	v_add_f32_e32 v146, v146, v147
	v_mul_f32_e32 v147, v25, v25
	v_mul_f32_e32 v170, v27, v27
	v_fmac_f32_e32 v147, v24, v24
	v_fmac_f32_e32 v170, v26, v26
	v_add_f32_e32 v147, v147, v170
	v_add_f32_e32 v28, v146, v147
	s_waitcnt vmcnt(11)
	v_fma_f32 v20, v20, 0.5, v226
	v_fma_f32 v21, v21, 0.5, v227
	v_fma_f32 v22, v22, 0.5, v228
	v_fma_f32 v23, v23, 0.5, v229
	v_fma_f32 v16, v16, 0.5, v230
	v_fma_f32 v17, v17, 0.5, v231
	v_fma_f32 v18, v18, 0.5, v232
	v_fma_f32 v19, v19, 0.5, v233
	v_cvt_pk_bf16_f32 v164, v20, v21
	v_cvt_pk_bf16_f32 v165, v22, v23
	v_cvt_pk_bf16_f32 v166, v16, v17
	v_cvt_pk_bf16_f32 v167, v18, v19
	global_store_dwordx4 v204, v[164:167], s[20:21] offset:256
	v_mul_f32_e32 v146, v21, v21
	v_mul_f32_e32 v147, v23, v23
	v_fmac_f32_e32 v146, v20, v20
	v_fmac_f32_e32 v147, v22, v22
	v_add_f32_e32 v146, v146, v147
	v_mul_f32_e32 v147, v17, v17
	v_mul_f32_e32 v170, v19, v19
	v_fmac_f32_e32 v147, v16, v16
	v_fmac_f32_e32 v170, v18, v18
	v_add_f32_e32 v147, v147, v170
	v_add_f32_e32 v146, v146, v147
	v_add_f32_e32 v16, v28, v146
	s_waitcnt vmcnt(9)
	v_fma_f32 v12, v12, 0.5, v128
	v_fma_f32 v13, v13, 0.5, v129
	v_fma_f32 v14, v14, 0.5, v130
	v_fma_f32 v15, v15, 0.5, v131
	v_fma_f32 v8, v8, 0.5, v132
	v_fma_f32 v9, v9, 0.5, v133
	v_fma_f32 v10, v10, 0.5, v134
	v_fma_f32 v11, v11, 0.5, v135
	v_cvt_pk_bf16_f32 v212, v12, v13
	v_cvt_pk_bf16_f32 v213, v14, v15
	v_cvt_pk_bf16_f32 v214, v8, v9
	v_cvt_pk_bf16_f32 v215, v10, v11
	global_store_dwordx4 v205, v[212:215], s[20:21]
	v_mul_f32_e32 v146, v13, v13
	v_mul_f32_e32 v147, v15, v15
	v_fmac_f32_e32 v146, v12, v12
	v_fmac_f32_e32 v147, v14, v14
	v_add_f32_e32 v146, v146, v147
	v_mul_f32_e32 v147, v9, v9
	v_mul_f32_e32 v170, v11, v11
	v_fmac_f32_e32 v147, v8, v8
	v_fmac_f32_e32 v170, v10, v10
	v_add_f32_e32 v147, v147, v170
	v_add_f32_e32 v12, v146, v147
	s_waitcnt vmcnt(7)
	v_fma_f32 v4, v4, 0.5, v150
	v_fma_f32 v5, v5, 0.5, v151
	v_fma_f32 v6, v6, 0.5, v152
	v_fma_f32 v7, v7, 0.5, v153
	v_fma_f32 v0, v0, 0.5, v154
	v_fma_f32 v1, v1, 0.5, v155
	v_fma_f32 v2, v2, 0.5, v156
	v_fma_f32 v3, v3, 0.5, v157
	v_cvt_pk_bf16_f32 v164, v4, v5
	v_cvt_pk_bf16_f32 v165, v6, v7
	v_cvt_pk_bf16_f32 v166, v0, v1
	v_cvt_pk_bf16_f32 v167, v2, v3
	global_store_dwordx4 v205, v[164:167], s[20:21] offset:256
	v_mul_f32_e32 v146, v5, v5
	v_mul_f32_e32 v147, v7, v7
	v_fmac_f32_e32 v146, v4, v4
	v_fmac_f32_e32 v147, v6, v6
	v_add_f32_e32 v146, v146, v147
	v_mul_f32_e32 v147, v1, v1
	v_mul_f32_e32 v170, v3, v3
	v_fmac_f32_e32 v147, v0, v0
	v_fmac_f32_e32 v170, v2, v2
	v_add_f32_e32 v147, v147, v170
	v_add_f32_e32 v146, v146, v147
	v_add_f32_e32 v0, v12, v146
	v_xor_b32_e32 v217, 16, v210
	v_xor_b32_e32 v248, 32, v210
	v_lshlrev_b32_e32 v217, 2, v217
	v_lshlrev_b32_e32 v248, 2, v248
	ds_bpermute_b32 v172, v217, v112
	ds_bpermute_b32 v176, v217, v96
	ds_bpermute_b32 v180, v217, v80
	ds_bpermute_b32 v184, v217, v64
	ds_bpermute_b32 v188, v217, v48
	ds_bpermute_b32 v192, v217, v32
	ds_bpermute_b32 v196, v217, v16
	ds_bpermute_b32 v200, v217, v0
	s_waitcnt lgkmcnt(0)
	v_add_f32_e32 v112, v112, v172
	v_add_f32_e32 v96, v96, v176
	v_add_f32_e32 v80, v80, v180
	v_add_f32_e32 v64, v64, v184
	v_add_f32_e32 v48, v48, v188
	v_add_f32_e32 v32, v32, v192
	v_add_f32_e32 v16, v16, v196
	v_add_f32_e32 v0, v0, v200
	ds_bpermute_b32 v172, v248, v112
	ds_bpermute_b32 v176, v248, v96
	ds_bpermute_b32 v180, v248, v80
	ds_bpermute_b32 v184, v248, v64
	ds_bpermute_b32 v188, v248, v48
	ds_bpermute_b32 v192, v248, v32
	ds_bpermute_b32 v196, v248, v16
	ds_bpermute_b32 v200, v248, v0
	s_waitcnt lgkmcnt(0)
	v_add_f32_e32 v112, v112, v172
	v_add_f32_e32 v96, v96, v176
	v_add_f32_e32 v80, v80, v180
	v_add_f32_e32 v64, v64, v184
	v_add_f32_e32 v48, v48, v188
	v_add_f32_e32 v32, v32, v192
	v_add_f32_e32 v16, v16, v196
	v_add_f32_e32 v0, v0, v200
	s_lshl_b32 s0, s10, 4
	s_lshl_b32 s2, s54, 2
	s_add_i32 s0, s0, s2
	v_lshlrev_b32_e32 v146, 6, v171
	v_add_u32_e32 v146, s0, v146
	v_add_u32_e32 v147, 0x2000, v146
	v_bfe_u32 v170, v206, 4, 2
	v_cmp_eq_u32_e64 s[0:1], 0, v170
	s_nop 3
	s_and_saveexec_b64 s[2:3], s[0:1]
	global_store_dword v146, v112, s[26:27]
	global_store_dword v146, v96, s[26:27] offset:1024
	global_store_dword v146, v80, s[26:27] offset:2048
	global_store_dword v146, v64, s[26:27] offset:3072
	global_store_dword v147, v48, s[26:27]
	global_store_dword v147, v32, s[26:27] offset:1024
	global_store_dword v147, v16, s[26:27] offset:2048
	global_store_dword v147, v0, s[26:27] offset:3072
	s_or_b64 exec, exec, s[2:3]
	s_branch .LBB0_523
.Ldown_epi_r1:
	global_load_dwordx4 v[172:175], v158, s[24:25]
	global_load_dwordx4 v[176:179], v158, s[24:25] offset:256
	global_load_dwordx4 v[180:183], v159, s[24:25]
	global_load_dwordx4 v[184:187], v159, s[24:25] offset:256
	global_load_dwordx4 v[188:191], v160, s[24:25]
	global_load_dwordx4 v[192:195], v160, s[24:25] offset:256
	global_load_dwordx4 v[196:199], v161, s[24:25]
	global_load_dwordx4 v[200:203], v161, s[24:25] offset:256
	global_load_dwordx4 v[218:221], v162, s[24:25]
	global_load_dwordx4 v[222:225], v162, s[24:25] offset:256
	global_load_dwordx4 v[226:229], v163, s[24:25]
	global_load_dwordx4 v[230:233], v163, s[24:25] offset:256
	global_load_dwordx4 v[128:131], v204, s[24:25]
	global_load_dwordx4 v[132:135], v204, s[24:25] offset:256
	global_load_dwordx4 v[150:153], v205, s[24:25]
	global_load_dwordx4 v[154:157], v205, s[24:25] offset:256
	v_lshlrev_b32_e32 v208, 1, v158
	s_waitcnt vmcnt(15)
	v_lshlrev_b32_e32 v146, 16, v172
	v_and_b32_e32 v147, 0xffff0000, v172
	v_fma_f32 v124, v124, 0.5, v146
	v_fma_f32 v125, v125, 0.5, v147
	v_lshlrev_b32_e32 v170, 16, v173
	v_and_b32_e32 v249, 0xffff0000, v173
	v_fma_f32 v126, v126, 0.5, v170
	v_fma_f32 v127, v127, 0.5, v249
	v_lshlrev_b32_e32 v146, 16, v174
	v_and_b32_e32 v147, 0xffff0000, v174
	v_fma_f32 v120, v120, 0.5, v146
	v_fma_f32 v121, v121, 0.5, v147
	v_lshlrev_b32_e32 v170, 16, v175
	v_and_b32_e32 v249, 0xffff0000, v175
	v_fma_f32 v122, v122, 0.5, v170
	v_fma_f32 v123, v123, 0.5, v249
	global_store_dwordx4 v208, v[124:127], s[18:19] nt
	global_store_dwordx4 v208, v[120:123], s[18:19] offset:16 nt
	s_waitcnt vmcnt(16)
	v_lshlrev_b32_e32 v146, 16, v176
	v_and_b32_e32 v147, 0xffff0000, v176
	v_fma_f32 v116, v116, 0.5, v146
	v_fma_f32 v117, v117, 0.5, v147
	v_lshlrev_b32_e32 v170, 16, v177
	v_and_b32_e32 v249, 0xffff0000, v177
	v_fma_f32 v118, v118, 0.5, v170
	v_fma_f32 v119, v119, 0.5, v249
	v_lshlrev_b32_e32 v146, 16, v178
	v_and_b32_e32 v147, 0xffff0000, v178
	v_fma_f32 v112, v112, 0.5, v146
	v_fma_f32 v113, v113, 0.5, v147
	v_lshlrev_b32_e32 v170, 16, v179
	v_and_b32_e32 v249, 0xffff0000, v179
	v_fma_f32 v114, v114, 0.5, v170
	v_fma_f32 v115, v115, 0.5, v249
	global_store_dwordx4 v208, v[116:119], s[18:19] offset:512 nt
	global_store_dwordx4 v208, v[112:115], s[18:19] offset:528 nt
	v_lshlrev_b32_e32 v209, 1, v159
	s_waitcnt vmcnt(17)
	v_lshlrev_b32_e32 v146, 16, v180
	v_and_b32_e32 v147, 0xffff0000, v180
	v_fma_f32 v108, v108, 0.5, v146
	v_fma_f32 v109, v109, 0.5, v147
	v_lshlrev_b32_e32 v170, 16, v181
	v_and_b32_e32 v249, 0xffff0000, v181
	v_fma_f32 v110, v110, 0.5, v170
	v_fma_f32 v111, v111, 0.5, v249
	v_lshlrev_b32_e32 v146, 16, v182
	v_and_b32_e32 v147, 0xffff0000, v182
	v_fma_f32 v104, v104, 0.5, v146
	v_fma_f32 v105, v105, 0.5, v147
	v_lshlrev_b32_e32 v170, 16, v183
	v_and_b32_e32 v249, 0xffff0000, v183
	v_fma_f32 v106, v106, 0.5, v170
	v_fma_f32 v107, v107, 0.5, v249
	global_store_dwordx4 v209, v[108:111], s[18:19] nt
	global_store_dwordx4 v209, v[104:107], s[18:19] offset:16 nt
	s_waitcnt vmcnt(18)
	v_lshlrev_b32_e32 v146, 16, v184
	v_and_b32_e32 v147, 0xffff0000, v184
	v_fma_f32 v100, v100, 0.5, v146
	v_fma_f32 v101, v101, 0.5, v147
	v_lshlrev_b32_e32 v170, 16, v185
	v_and_b32_e32 v249, 0xffff0000, v185
	v_fma_f32 v102, v102, 0.5, v170
	v_fma_f32 v103, v103, 0.5, v249
	v_lshlrev_b32_e32 v146, 16, v186
	v_and_b32_e32 v147, 0xffff0000, v186
	v_fma_f32 v96, v96, 0.5, v146
	v_fma_f32 v97, v97, 0.5, v147
	v_lshlrev_b32_e32 v170, 16, v187
	v_and_b32_e32 v249, 0xffff0000, v187
	v_fma_f32 v98, v98, 0.5, v170
	v_fma_f32 v99, v99, 0.5, v249
	global_store_dwordx4 v209, v[100:103], s[18:19] offset:512 nt
	global_store_dwordx4 v209, v[96:99], s[18:19] offset:528 nt
	v_lshlrev_b32_e32 v208, 1, v160
	s_waitcnt vmcnt(19)
	v_lshlrev_b32_e32 v146, 16, v188
	v_and_b32_e32 v147, 0xffff0000, v188
	v_fma_f32 v92, v92, 0.5, v146
	v_fma_f32 v93, v93, 0.5, v147
	v_lshlrev_b32_e32 v170, 16, v189
	v_and_b32_e32 v249, 0xffff0000, v189
	v_fma_f32 v94, v94, 0.5, v170
	v_fma_f32 v95, v95, 0.5, v249
	v_lshlrev_b32_e32 v146, 16, v190
	v_and_b32_e32 v147, 0xffff0000, v190
	v_fma_f32 v88, v88, 0.5, v146
	v_fma_f32 v89, v89, 0.5, v147
	v_lshlrev_b32_e32 v170, 16, v191
	v_and_b32_e32 v249, 0xffff0000, v191
	v_fma_f32 v90, v90, 0.5, v170
	v_fma_f32 v91, v91, 0.5, v249
	global_store_dwordx4 v208, v[92:95], s[18:19] nt
	global_store_dwordx4 v208, v[88:91], s[18:19] offset:16 nt
	s_waitcnt vmcnt(20)
	v_lshlrev_b32_e32 v146, 16, v192
	v_and_b32_e32 v147, 0xffff0000, v192
	v_fma_f32 v84, v84, 0.5, v146
	v_fma_f32 v85, v85, 0.5, v147
	v_lshlrev_b32_e32 v170, 16, v193
	v_and_b32_e32 v249, 0xffff0000, v193
	v_fma_f32 v86, v86, 0.5, v170
	v_fma_f32 v87, v87, 0.5, v249
	v_lshlrev_b32_e32 v146, 16, v194
	v_and_b32_e32 v147, 0xffff0000, v194
	v_fma_f32 v80, v80, 0.5, v146
	v_fma_f32 v81, v81, 0.5, v147
	v_lshlrev_b32_e32 v170, 16, v195
	v_and_b32_e32 v249, 0xffff0000, v195
	v_fma_f32 v82, v82, 0.5, v170
	v_fma_f32 v83, v83, 0.5, v249
	global_store_dwordx4 v208, v[84:87], s[18:19] offset:512 nt
	global_store_dwordx4 v208, v[80:83], s[18:19] offset:528 nt
	v_lshlrev_b32_e32 v209, 1, v161
	s_waitcnt vmcnt(21)
	v_lshlrev_b32_e32 v146, 16, v196
	v_and_b32_e32 v147, 0xffff0000, v196
	v_fma_f32 v76, v76, 0.5, v146
	v_fma_f32 v77, v77, 0.5, v147
	v_lshlrev_b32_e32 v170, 16, v197
	v_and_b32_e32 v249, 0xffff0000, v197
	v_fma_f32 v78, v78, 0.5, v170
	v_fma_f32 v79, v79, 0.5, v249
	v_lshlrev_b32_e32 v146, 16, v198
	v_and_b32_e32 v147, 0xffff0000, v198
	v_fma_f32 v72, v72, 0.5, v146
	v_fma_f32 v73, v73, 0.5, v147
	v_lshlrev_b32_e32 v170, 16, v199
	v_and_b32_e32 v249, 0xffff0000, v199
	v_fma_f32 v74, v74, 0.5, v170
	v_fma_f32 v75, v75, 0.5, v249
	global_store_dwordx4 v209, v[76:79], s[18:19] nt
	global_store_dwordx4 v209, v[72:75], s[18:19] offset:16 nt
	s_waitcnt vmcnt(22)
	v_lshlrev_b32_e32 v146, 16, v200
	v_and_b32_e32 v147, 0xffff0000, v200
	v_fma_f32 v68, v68, 0.5, v146
	v_fma_f32 v69, v69, 0.5, v147
	v_lshlrev_b32_e32 v170, 16, v201
	v_and_b32_e32 v249, 0xffff0000, v201
	v_fma_f32 v70, v70, 0.5, v170
	v_fma_f32 v71, v71, 0.5, v249
	v_lshlrev_b32_e32 v146, 16, v202
	v_and_b32_e32 v147, 0xffff0000, v202
	v_fma_f32 v64, v64, 0.5, v146
	v_fma_f32 v65, v65, 0.5, v147
	v_lshlrev_b32_e32 v170, 16, v203
	v_and_b32_e32 v249, 0xffff0000, v203
	v_fma_f32 v66, v66, 0.5, v170
	v_fma_f32 v67, v67, 0.5, v249
	global_store_dwordx4 v209, v[68:71], s[18:19] offset:512 nt
	global_store_dwordx4 v209, v[64:67], s[18:19] offset:528 nt
	v_lshlrev_b32_e32 v208, 1, v162
	s_waitcnt vmcnt(23)
	v_lshlrev_b32_e32 v146, 16, v218
	v_and_b32_e32 v147, 0xffff0000, v218
	v_fma_f32 v60, v60, 0.5, v146
	v_fma_f32 v61, v61, 0.5, v147
	v_lshlrev_b32_e32 v170, 16, v219
	v_and_b32_e32 v249, 0xffff0000, v219
	v_fma_f32 v62, v62, 0.5, v170
	v_fma_f32 v63, v63, 0.5, v249
	v_lshlrev_b32_e32 v146, 16, v220
	v_and_b32_e32 v147, 0xffff0000, v220
	v_fma_f32 v56, v56, 0.5, v146
	v_fma_f32 v57, v57, 0.5, v147
	v_lshlrev_b32_e32 v170, 16, v221
	v_and_b32_e32 v249, 0xffff0000, v221
	v_fma_f32 v58, v58, 0.5, v170
	v_fma_f32 v59, v59, 0.5, v249
	global_store_dwordx4 v208, v[60:63], s[18:19] nt
	global_store_dwordx4 v208, v[56:59], s[18:19] offset:16 nt
	s_waitcnt vmcnt(24)
	v_lshlrev_b32_e32 v146, 16, v222
	v_and_b32_e32 v147, 0xffff0000, v222
	v_fma_f32 v52, v52, 0.5, v146
	v_fma_f32 v53, v53, 0.5, v147
	v_lshlrev_b32_e32 v170, 16, v223
	v_and_b32_e32 v249, 0xffff0000, v223
	v_fma_f32 v54, v54, 0.5, v170
	v_fma_f32 v55, v55, 0.5, v249
	v_lshlrev_b32_e32 v146, 16, v224
	v_and_b32_e32 v147, 0xffff0000, v224
	v_fma_f32 v48, v48, 0.5, v146
	v_fma_f32 v49, v49, 0.5, v147
	v_lshlrev_b32_e32 v170, 16, v225
	v_and_b32_e32 v249, 0xffff0000, v225
	v_fma_f32 v50, v50, 0.5, v170
	v_fma_f32 v51, v51, 0.5, v249
	global_store_dwordx4 v208, v[52:55], s[18:19] offset:512 nt
	global_store_dwordx4 v208, v[48:51], s[18:19] offset:528 nt
	v_lshlrev_b32_e32 v209, 1, v163
	s_waitcnt vmcnt(25)
	v_lshlrev_b32_e32 v146, 16, v226
	v_and_b32_e32 v147, 0xffff0000, v226
	v_fma_f32 v44, v44, 0.5, v146
	v_fma_f32 v45, v45, 0.5, v147
	v_lshlrev_b32_e32 v170, 16, v227
	v_and_b32_e32 v249, 0xffff0000, v227
	v_fma_f32 v46, v46, 0.5, v170
	v_fma_f32 v47, v47, 0.5, v249
	v_lshlrev_b32_e32 v146, 16, v228
	v_and_b32_e32 v147, 0xffff0000, v228
	v_fma_f32 v40, v40, 0.5, v146
	v_fma_f32 v41, v41, 0.5, v147
	v_lshlrev_b32_e32 v170, 16, v229
	v_and_b32_e32 v249, 0xffff0000, v229
	v_fma_f32 v42, v42, 0.5, v170
	v_fma_f32 v43, v43, 0.5, v249
	global_store_dwordx4 v209, v[44:47], s[18:19] nt
	global_store_dwordx4 v209, v[40:43], s[18:19] offset:16 nt
	s_waitcnt vmcnt(26)
	v_lshlrev_b32_e32 v146, 16, v230
	v_and_b32_e32 v147, 0xffff0000, v230
	v_fma_f32 v36, v36, 0.5, v146
	v_fma_f32 v37, v37, 0.5, v147
	v_lshlrev_b32_e32 v170, 16, v231
	v_and_b32_e32 v249, 0xffff0000, v231
	v_fma_f32 v38, v38, 0.5, v170
	v_fma_f32 v39, v39, 0.5, v249
	v_lshlrev_b32_e32 v146, 16, v232
	v_and_b32_e32 v147, 0xffff0000, v232
	v_fma_f32 v32, v32, 0.5, v146
	v_fma_f32 v33, v33, 0.5, v147
	v_lshlrev_b32_e32 v170, 16, v233
	v_and_b32_e32 v249, 0xffff0000, v233
	v_fma_f32 v34, v34, 0.5, v170
	v_fma_f32 v35, v35, 0.5, v249
	global_store_dwordx4 v209, v[36:39], s[18:19] offset:512 nt
	global_store_dwordx4 v209, v[32:35], s[18:19] offset:528 nt
	v_lshlrev_b32_e32 v208, 1, v204
	s_waitcnt vmcnt(27)
	v_lshlrev_b32_e32 v146, 16, v128
	v_and_b32_e32 v147, 0xffff0000, v128
	v_fma_f32 v28, v28, 0.5, v146
	v_fma_f32 v29, v29, 0.5, v147
	v_lshlrev_b32_e32 v170, 16, v129
	v_and_b32_e32 v249, 0xffff0000, v129
	v_fma_f32 v30, v30, 0.5, v170
	v_fma_f32 v31, v31, 0.5, v249
	v_lshlrev_b32_e32 v146, 16, v130
	v_and_b32_e32 v147, 0xffff0000, v130
	v_fma_f32 v24, v24, 0.5, v146
	v_fma_f32 v25, v25, 0.5, v147
	v_lshlrev_b32_e32 v170, 16, v131
	v_and_b32_e32 v249, 0xffff0000, v131
	v_fma_f32 v26, v26, 0.5, v170
	v_fma_f32 v27, v27, 0.5, v249
	global_store_dwordx4 v208, v[28:31], s[18:19] nt
	global_store_dwordx4 v208, v[24:27], s[18:19] offset:16 nt
	s_waitcnt vmcnt(28)
	v_lshlrev_b32_e32 v146, 16, v132
	v_and_b32_e32 v147, 0xffff0000, v132
	v_fma_f32 v20, v20, 0.5, v146
	v_fma_f32 v21, v21, 0.5, v147
	v_lshlrev_b32_e32 v170, 16, v133
	v_and_b32_e32 v249, 0xffff0000, v133
	v_fma_f32 v22, v22, 0.5, v170
	v_fma_f32 v23, v23, 0.5, v249
	v_lshlrev_b32_e32 v146, 16, v134
	v_and_b32_e32 v147, 0xffff0000, v134
	v_fma_f32 v16, v16, 0.5, v146
	v_fma_f32 v17, v17, 0.5, v147
	v_lshlrev_b32_e32 v170, 16, v135
	v_and_b32_e32 v249, 0xffff0000, v135
	v_fma_f32 v18, v18, 0.5, v170
	v_fma_f32 v19, v19, 0.5, v249
	global_store_dwordx4 v208, v[20:23], s[18:19] offset:512 nt
	global_store_dwordx4 v208, v[16:19], s[18:19] offset:528 nt
	v_lshlrev_b32_e32 v209, 1, v205
	s_waitcnt vmcnt(29)
	v_lshlrev_b32_e32 v146, 16, v150
	v_and_b32_e32 v147, 0xffff0000, v150
	v_fma_f32 v12, v12, 0.5, v146
	v_fma_f32 v13, v13, 0.5, v147
	v_lshlrev_b32_e32 v170, 16, v151
	v_and_b32_e32 v249, 0xffff0000, v151
	v_fma_f32 v14, v14, 0.5, v170
	v_fma_f32 v15, v15, 0.5, v249
	v_lshlrev_b32_e32 v146, 16, v152
	v_and_b32_e32 v147, 0xffff0000, v152
	v_fma_f32 v8, v8, 0.5, v146
	v_fma_f32 v9, v9, 0.5, v147
	v_lshlrev_b32_e32 v170, 16, v153
	v_and_b32_e32 v249, 0xffff0000, v153
	v_fma_f32 v10, v10, 0.5, v170
	v_fma_f32 v11, v11, 0.5, v249
	global_store_dwordx4 v209, v[12:15], s[18:19] nt
	global_store_dwordx4 v209, v[8:11], s[18:19] offset:16 nt
	s_waitcnt vmcnt(30)
	v_lshlrev_b32_e32 v146, 16, v154
	v_and_b32_e32 v147, 0xffff0000, v154
	v_fma_f32 v4, v4, 0.5, v146
	v_fma_f32 v5, v5, 0.5, v147
	v_lshlrev_b32_e32 v170, 16, v155
	v_and_b32_e32 v249, 0xffff0000, v155
	v_fma_f32 v6, v6, 0.5, v170
	v_fma_f32 v7, v7, 0.5, v249
	v_lshlrev_b32_e32 v146, 16, v156
	v_and_b32_e32 v147, 0xffff0000, v156
	v_fma_f32 v0, v0, 0.5, v146
	v_fma_f32 v1, v1, 0.5, v147
	v_lshlrev_b32_e32 v170, 16, v157
	v_and_b32_e32 v249, 0xffff0000, v157
	v_fma_f32 v2, v2, 0.5, v170
	v_fma_f32 v3, v3, 0.5, v249
	global_store_dwordx4 v209, v[4:7], s[18:19] offset:512 nt
	global_store_dwordx4 v209, v[0:3], s[18:19] offset:528 nt
